# FFN-up epilogue: first 8-byte half of each output row parked in LDS (idle SA(1,1) slice + 16 KiB static LDS), one dwordx4 store per row instead of two dwordx2
# speedup vs baseline: 1.0065x; 1.0065x over previous
; __device__ __forceinline__ unsigned cvtpk(float lo, float hi) { f32x2_t v = {lo, hi}; bf16x2_t b = __builtin_convertvector(v, bf16x2_t); return __builtin_bit_cast(unsigned, b); }
;     __device__ __forceinline__ void operator()(f32x4 (&acc)[2][2][4][2], const Unit& u, int wr, int wc, int fr, int fq) const {
;     ...
;                         float a[2];
; #pragma unroll
;                         for (int jj = 0; jj < 2; ++jj) { const float g = uu[0][jj]; a[jj] = g * uu[1][jj] * __builtin_amdgcn_rcpf(1.f + __builtin_amdgcn_exp2f(-g * LOG2E)); }
;                         const unsigned pk = cvtpk(a[0], a[1]);
;                         if (jh == 0) stash[ai][m] = pk;
;                         else if (rr >= 1 && rr <= 62 && tok < ntok) { u32x2 w; w.x = stash[ai][m]; w.y = pk; *(u32x2*)(obase + (size_t)tok * FFN + 4 * n) = w; }
.LBB0_807:
	s_lshl_b32 s6, s20, 7
	s_ashr_i32 s7, s6, 31
	v_lshl_add_u64 v[78:79], s[6:7], 1, v[196:197]
	v_readlane_b32 s6, v255, 21
	v_cmp_gt_i32_e32 vcc, s31, v249
	v_readlane_b32 s7, v255, 22
	s_and_b64 s[40:41], s[6:7], vcc
	v_mbcnt_lo_u32_b32 v250, -1, 0
	v_mbcnt_hi_u32_b32 v250, -1, v250
	v_lshlrev_b32_e32 v250, 3, v250
	v_mov_b32_e32 v251, s11
	v_lshl_add_u32 v251, v251, 1, v250
	v_add_u32_e32 v251, 0x21040, v251
	v_add_u32_e32 v250, s11, v250
	v_add_u32_e32 v250, 0xc000, v250
	s_waitcnt vmcnt(0)
	s_and_saveexec_b64 s[6:7], s[40:41]
	s_cbranch_execz .LBB0_809
	v_mul_f32_e32 v87, 0xbfb8aa3b, v220
	v_exp_f32_e32 v87, v87
	v_pk_mul_f32 v[160:161], v[160:161], v[152:153]
	v_pk_mul_f32 v[180:181], v[222:223], v[220:221]
	s_movk_i32 s15, 0x1600
	v_add_f32_e32 v87, 1.0, v87
	v_rcp_f32_e32 v172, v87
	v_mul_f32_e32 v87, 0xbfb8aa3b, v221
	v_exp_f32_e32 v87, v87
	s_nop 0
	v_add_f32_e32 v87, 1.0, v87
	v_rcp_f32_e32 v173, v87
	v_mul_f32_e32 v87, 0xbfb8aa3b, v152
	v_exp_f32_e32 v87, v87
	v_pk_mul_f32 v[172:173], v[180:181], v[172:173]
	s_nop 0
	v_cvt_pk_bf16_f32 v172, v172, v173
	v_add_f32_e32 v87, 1.0, v87
	v_rcp_f32_e32 v152, v87
	v_mul_f32_e32 v87, 0xbfb8aa3b, v153
	v_exp_f32_e32 v87, v87
	s_nop 0
	v_add_f32_e32 v87, 1.0, v87
	v_rcp_f32_e32 v153, v87
	s_nop 0
	v_pk_mul_f32 v[152:153], v[160:161], v[152:153]
	s_nop 0
	v_cvt_pk_bf16_f32 v173, v152, v153
	v_mad_i64_i32 v[152:153], s[20:21], v249, s15, v[78:79]
	ds_write_b64 v250, v[172:173]

; __device__ __forceinline__ unsigned cvtpk(float lo, float hi) { f32x2_t v = {lo, hi}; bf16x2_t b = __builtin_convertvector(v, bf16x2_t); return __builtin_bit_cast(unsigned, b); }
;     __device__ __forceinline__ void operator()(f32x4 (&acc)[2][2][4][2], const Unit& u, int wr, int wc, int fr, int fq) const {
;     ...
;                         float a[2];
; #pragma unroll
;                         for (int jj = 0; jj < 2; ++jj) { const float g = uu[0][jj]; a[jj] = g * uu[1][jj] * __builtin_amdgcn_rcpf(1.f + __builtin_amdgcn_exp2f(-g * LOG2E)); }
;                         const unsigned pk = cvtpk(a[0], a[1]);
;                         if (jh == 0) stash[ai][m] = pk;
;                         else if (rr >= 1 && rr <= 62 && tok < ntok) { u32x2 w; w.x = stash[ai][m]; w.y = pk; *(u32x2*)(obase + (size_t)tok * FFN + 4 * n) = w; }
.LBB0_811:
	v_cmp_gt_i32_e64 s[90:91], s31, v248
	s_and_saveexec_b64 s[6:7], s[90:91]
	s_cbranch_execz .LBB0_813
	v_mul_f32_e32 v156, 0xbfb8aa3b, v216
	v_mul_f32_e32 v157, 0xbfb8aa3b, v217
	v_pk_mul_f32 v[160:161], v[160:161], v[152:153]
	v_mul_f32_e32 v152, 0xbfb8aa3b, v152
	v_mul_f32_e32 v153, 0xbfb8aa3b, v153
	v_exp_f32_e32 v156, v156
	v_exp_f32_e32 v157, v157
	v_exp_f32_e32 v152, v152
	v_exp_f32_e32 v153, v153
	v_add_f32_e32 v156, 1.0, v156
	v_add_f32_e32 v157, 1.0, v157
	v_add_f32_e32 v152, 1.0, v152
	v_add_f32_e32 v153, 1.0, v153
	v_rcp_f32_e32 v156, v156
	v_rcp_f32_e32 v157, v157
	v_rcp_f32_e32 v152, v152
	v_rcp_f32_e32 v153, v153
	v_pk_mul_f32 v[164:165], v[218:219], v[216:217]
	s_movk_i32 s15, 0x1600
	v_pk_mul_f32 v[156:157], v[164:165], v[156:157]
	v_pk_mul_f32 v[152:153], v[160:161], v[152:153]
	v_cvt_pk_bf16_f32 v156, v156, v157
	v_cvt_pk_bf16_f32 v157, v152, v153
	v_mad_i64_i32 v[152:153], s[20:21], v248, s15, v[78:79]
	ds_write_b64 v250, v[156:157] offset:512

; __device__ __forceinline__ unsigned cvtpk(float lo, float hi) { f32x2_t v = {lo, hi}; bf16x2_t b = __builtin_convertvector(v, bf16x2_t); return __builtin_bit_cast(unsigned, b); }
;     __device__ __forceinline__ void operator()(f32x4 (&acc)[2][2][4][2], const Unit& u, int wr, int wc, int fr, int fq) const {
;     ...
;                         float a[2];
; #pragma unroll
;                         for (int jj = 0; jj < 2; ++jj) { const float g = uu[0][jj]; a[jj] = g * uu[1][jj] * __builtin_amdgcn_rcpf(1.f + __builtin_amdgcn_exp2f(-g * LOG2E)); }
;                         const unsigned pk = cvtpk(a[0], a[1]);
;                         if (jh == 0) stash[ai][m] = pk;
;                         else if (rr >= 1 && rr <= 62 && tok < ntok) { u32x2 w; w.x = stash[ai][m]; w.y = pk; *(u32x2*)(obase + (size_t)tok * FFN + 4 * n) = w; }
.LBB0_815:
	v_cmp_gt_i32_e64 s[88:89], s31, v225
	s_and_saveexec_b64 s[6:7], s[88:89]
	s_cbranch_execz .LBB0_817
	v_mul_f32_e32 v118, 0xbfb8aa3b, v186
	v_mul_f32_e32 v119, 0xbfb8aa3b, v187
	v_exp_f32_e32 v118, v118
	v_exp_f32_e32 v119, v119
	v_pk_mul_f32 v[122:123], v[188:189], v[186:187]
	s_movk_i32 s15, 0x1600
	v_add_f32_e32 v118, 1.0, v118
	v_add_f32_e32 v119, 1.0, v119
	v_rcp_f32_e32 v118, v118
	v_rcp_f32_e32 v119, v119
	s_nop 0
	v_pk_mul_f32 v[118:119], v[122:123], v[118:119]
	s_nop 0
	v_cvt_pk_bf16_f32 v118, v118, v119
	v_mul_f32_e32 v119, 0xbfb8aa3b, v152
	v_exp_f32_e32 v119, v119
	v_pk_mul_f32 v[122:123], v[156:157], v[152:153]
	v_add_f32_e32 v119, 1.0, v119
	v_rcp_f32_e32 v152, v119
	v_mul_f32_e32 v119, 0xbfb8aa3b, v153
	v_exp_f32_e32 v119, v119
	s_nop 0
	v_add_f32_e32 v119, 1.0, v119
	v_rcp_f32_e32 v153, v119
	s_nop 0
	v_pk_mul_f32 v[122:123], v[122:123], v[152:153]
	s_nop 0
	v_cvt_pk_bf16_f32 v119, v122, v123
	v_mad_i64_i32 v[122:123], s[20:21], v225, s15, v[78:79]
	ds_write_b64 v250, v[118:119] offset:8192

; __device__ __forceinline__ unsigned cvtpk(float lo, float hi) { f32x2_t v = {lo, hi}; bf16x2_t b = __builtin_convertvector(v, bf16x2_t); return __builtin_bit_cast(unsigned, b); }
;     __device__ __forceinline__ void operator()(f32x4 (&acc)[2][2][4][2], const Unit& u, int wr, int wc, int fr, int fq) const {
;     ...
;                         float a[2];
; #pragma unroll
;                         for (int jj = 0; jj < 2; ++jj) { const float g = uu[0][jj]; a[jj] = g * uu[1][jj] * __builtin_amdgcn_rcpf(1.f + __builtin_amdgcn_exp2f(-g * LOG2E)); }
;                         const unsigned pk = cvtpk(a[0], a[1]);
;                         if (jh == 0) stash[ai][m] = pk;
;                         else if (rr >= 1 && rr <= 62 && tok < ntok) { u32x2 w; w.x = stash[ai][m]; w.y = pk; *(u32x2*)(obase + (size_t)tok * FFN + 4 * n) = w; }
.LBB0_819:
	v_cmp_gt_i32_e32 vcc, s31, v224
	s_and_b64 s[22:23], s[48:49], vcc
	s_and_saveexec_b64 s[6:7], s[22:23]
	s_cbranch_execz .LBB0_821
	v_mul_f32_e32 v136, 0xbfb8aa3b, v182
	v_mul_f32_e32 v137, 0xbfb8aa3b, v183
	v_pk_mul_f32 v[122:123], v[122:123], v[118:119]
	v_mul_f32_e32 v118, 0xbfb8aa3b, v118
	v_mul_f32_e32 v119, 0xbfb8aa3b, v119
	v_exp_f32_e32 v136, v136
	v_exp_f32_e32 v137, v137
	v_exp_f32_e32 v118, v118
	v_exp_f32_e32 v119, v119
	v_add_f32_e32 v136, 1.0, v136
	v_add_f32_e32 v137, 1.0, v137
	v_add_f32_e32 v118, 1.0, v118
	v_add_f32_e32 v119, 1.0, v119
	v_rcp_f32_e32 v136, v136
	v_rcp_f32_e32 v137, v137
	v_rcp_f32_e32 v118, v118
	v_rcp_f32_e32 v119, v119
	v_pk_mul_f32 v[140:141], v[184:185], v[182:183]
	s_movk_i32 s15, 0x1600
	v_pk_mul_f32 v[136:137], v[140:141], v[136:137]
	v_pk_mul_f32 v[118:119], v[122:123], v[118:119]
	v_cvt_pk_bf16_f32 v136, v136, v137
	v_cvt_pk_bf16_f32 v137, v118, v119
	v_mad_i64_i32 v[118:119], s[20:21], v224, s15, v[78:79]
	ds_write_b64 v250, v[136:137] offset:8704

; __device__ __forceinline__ unsigned cvtpk(float lo, float hi) { f32x2_t v = {lo, hi}; bf16x2_t b = __builtin_convertvector(v, bf16x2_t); return __builtin_bit_cast(unsigned, b); }
;     __device__ __forceinline__ void operator()(f32x4 (&acc)[2][2][4][2], const Unit& u, int wr, int wc, int fr, int fq) const {
;     ...
;                         float a[2];
; #pragma unroll
;                         for (int jj = 0; jj < 2; ++jj) { const float g = uu[0][jj]; a[jj] = g * uu[1][jj] * __builtin_amdgcn_rcpf(1.f + __builtin_amdgcn_exp2f(-g * LOG2E)); }
;                         const unsigned pk = cvtpk(a[0], a[1]);
;                         if (jh == 0) stash[ai][m] = pk;
;                         else if (rr >= 1 && rr <= 62 && tok < ntok) { u32x2 w; w.x = stash[ai][m]; w.y = pk; *(u32x2*)(obase + (size_t)tok * FFN + 4 * n) = w; }
.LBB0_823:
	v_readlane_b32 s6, v255, 21
	v_cmp_gt_i32_e32 vcc, s31, v178
	v_readlane_b32 s7, v255, 22
	s_and_b64 s[20:21], s[6:7], vcc
	s_and_saveexec_b64 s[6:7], s[20:21]
	s_cbranch_execz .LBB0_825
	v_mul_f32_e32 v136, 0xbfb8aa3b, v174
	v_exp_f32_e32 v136, v136
	v_pk_mul_f32 v[122:123], v[122:123], v[96:97]
	v_mul_f32_e32 v96, 0xbfb8aa3b, v96
	v_mul_f32_e32 v97, 0xbfb8aa3b, v97
	v_add_f32_e32 v136, 1.0, v136
	v_rcp_f32_e32 v140, v136
	v_mul_f32_e32 v136, 0xbfb8aa3b, v175
	v_exp_f32_e32 v136, v136
	v_exp_f32_e32 v96, v96
	v_exp_f32_e32 v97, v97
	v_pk_mul_f32 v[144:145], v[176:177], v[174:175]
	v_add_f32_e32 v136, 1.0, v136
	v_add_f32_e32 v96, 1.0, v96
	v_add_f32_e32 v97, 1.0, v97
	v_rcp_f32_e32 v141, v136
	v_rcp_f32_e32 v96, v96
	v_rcp_f32_e32 v97, v97
	s_movk_i32 s15, 0x1600
	v_pk_mul_f32 v[140:141], v[144:145], v[140:141]
	v_pk_mul_f32 v[96:97], v[122:123], v[96:97]
	v_cvt_pk_bf16_f32 v140, v140, v141
	v_cvt_pk_bf16_f32 v141, v96, v97
	v_mad_i64_i32 v[96:97], s[94:95], v178, s15, v[78:79]
	ds_write_b64 v251, v[140:141]

; __device__ __forceinline__ unsigned cvtpk(float lo, float hi) { f32x2_t v = {lo, hi}; bf16x2_t b = __builtin_convertvector(v, bf16x2_t); return __builtin_bit_cast(unsigned, b); }
;     __device__ __forceinline__ void operator()(f32x4 (&acc)[2][2][4][2], const Unit& u, int wr, int wc, int fr, int fq) const {
;     ...
;                         float a[2];
; #pragma unroll
;                         for (int jj = 0; jj < 2; ++jj) { const float g = uu[0][jj]; a[jj] = g * uu[1][jj] * __builtin_amdgcn_rcpf(1.f + __builtin_amdgcn_exp2f(-g * LOG2E)); }
;                         const unsigned pk = cvtpk(a[0], a[1]);
;                         if (jh == 0) stash[ai][m] = pk;
;                         else if (rr >= 1 && rr <= 62 && tok < ntok) { u32x2 w; w.x = stash[ai][m]; w.y = pk; *(u32x2*)(obase + (size_t)tok * FFN + 4 * n) = w; }
.LBB0_827:
	v_cmp_gt_i32_e64 s[86:87], s31, v170
	s_and_saveexec_b64 s[6:7], s[86:87]
	s_cbranch_execz .LBB0_829
	v_mul_f32_e32 v100, 0xbfb8aa3b, v158
	v_mul_f32_e32 v101, 0xbfb8aa3b, v159
	v_exp_f32_e32 v100, v100
	v_exp_f32_e32 v101, v101
	v_pk_mul_f32 v[118:119], v[162:163], v[158:159]
	s_movk_i32 s15, 0x1600
	v_add_f32_e32 v100, 1.0, v100
	v_add_f32_e32 v101, 1.0, v101
	v_rcp_f32_e32 v100, v100
	v_rcp_f32_e32 v101, v101
	s_nop 0
	v_pk_mul_f32 v[100:101], v[118:119], v[100:101]
	v_pk_mul_f32 v[118:119], v[122:123], v[96:97]
	v_mul_f32_e32 v96, 0xbfb8aa3b, v96
	v_mul_f32_e32 v97, 0xbfb8aa3b, v97
	v_exp_f32_e32 v96, v96
	v_exp_f32_e32 v97, v97
	v_cvt_pk_bf16_f32 v100, v100, v101
	v_add_f32_e32 v96, 1.0, v96
	v_add_f32_e32 v97, 1.0, v97
	v_rcp_f32_e32 v96, v96
	v_rcp_f32_e32 v97, v97
	s_nop 0
	v_pk_mul_f32 v[96:97], v[118:119], v[96:97]
	s_nop 0
	v_cvt_pk_bf16_f32 v101, v96, v97
	v_mad_i64_i32 v[96:97], s[94:95], v170, s15, v[78:79]
	ds_write_b64 v251, v[100:101] offset:512

; __device__ __forceinline__ unsigned cvtpk(float lo, float hi) { f32x2_t v = {lo, hi}; bf16x2_t b = __builtin_convertvector(v, bf16x2_t); return __builtin_bit_cast(unsigned, b); }
;     __device__ __forceinline__ void operator()(f32x4 (&acc)[2][2][4][2], const Unit& u, int wr, int wc, int fr, int fq) const {
;     ...
;                         float a[2];
; #pragma unroll
;                         for (int jj = 0; jj < 2; ++jj) { const float g = uu[0][jj]; a[jj] = g * uu[1][jj] * __builtin_amdgcn_rcpf(1.f + __builtin_amdgcn_exp2f(-g * LOG2E)); }
;                         const unsigned pk = cvtpk(a[0], a[1]);
;                         if (jh == 0) stash[ai][m] = pk;
;                         else if (rr >= 1 && rr <= 62 && tok < ntok) { u32x2 w; w.x = stash[ai][m]; w.y = pk; *(u32x2*)(obase + (size_t)tok * FFN + 4 * n) = w; }
.LBB0_831:
	v_cmp_gt_i32_e64 s[84:85], s31, v169
	s_and_saveexec_b64 s[6:7], s[84:85]
	s_cbranch_execz .LBB0_833
	v_mul_f32_e32 v83, 0xbfb8aa3b, v138
	v_exp_f32_e32 v83, v83
	v_pk_mul_f32 v[92:93], v[146:147], v[138:139]
	s_movk_i32 s15, 0x1600
	v_add_f32_e32 v83, 1.0, v83
	v_rcp_f32_e32 v88, v83
	v_mul_f32_e32 v83, 0xbfb8aa3b, v139
	v_exp_f32_e32 v83, v83
	s_nop 0
	v_add_f32_e32 v83, 1.0, v83
	v_rcp_f32_e32 v89, v83
	v_mul_f32_e32 v83, 0xbfb8aa3b, v96
	v_exp_f32_e32 v83, v83
	v_pk_mul_f32 v[88:89], v[92:93], v[88:89]
	v_pk_mul_f32 v[92:93], v[100:101], v[96:97]
	v_add_f32_e32 v83, 1.0, v83
	v_rcp_f32_e32 v96, v83
	v_mul_f32_e32 v83, 0xbfb8aa3b, v97
	v_exp_f32_e32 v83, v83
	v_cvt_pk_bf16_f32 v88, v88, v89
	v_add_f32_e32 v83, 1.0, v83
	v_rcp_f32_e32 v97, v83
	s_nop 0
	v_pk_mul_f32 v[92:93], v[92:93], v[96:97]
	s_nop 0
	v_cvt_pk_bf16_f32 v89, v92, v93
	v_mad_i64_i32 v[92:93], s[94:95], v169, s15, v[78:79]
	ds_write_b64 v251, v[88:89] offset:1024

; __device__ __forceinline__ unsigned cvtpk(float lo, float hi) { f32x2_t v = {lo, hi}; bf16x2_t b = __builtin_convertvector(v, bf16x2_t); return __builtin_bit_cast(unsigned, b); }
;     __device__ __forceinline__ void operator()(f32x4 (&acc)[2][2][4][2], const Unit& u, int wr, int wc, int fr, int fq) const {
;     ...
;                         float a[2];
; #pragma unroll
;                         for (int jj = 0; jj < 2; ++jj) { const float g = uu[0][jj]; a[jj] = g * uu[1][jj] * __builtin_amdgcn_rcpf(1.f + __builtin_amdgcn_exp2f(-g * LOG2E)); }
;                         const unsigned pk = cvtpk(a[0], a[1]);
;                         if (jh == 0) stash[ai][m] = pk;
;                         else if (rr >= 1 && rr <= 62 && tok < ntok) { u32x2 w; w.x = stash[ai][m]; w.y = pk; *(u32x2*)(obase + (size_t)tok * FFN + 4 * n) = w; }
.LBB0_835:
	v_cmp_gt_i32_e32 vcc, s31, v168
	s_and_b64 s[6:7], s[48:49], vcc
	s_and_saveexec_b64 s[92:93], s[6:7]
	s_cbranch_execz .LBB0_837
	v_mul_f32_e32 v72, 0xbfb8aa3b, v130
	v_mul_f32_e32 v73, 0xbfb8aa3b, v131
	v_exp_f32_e32 v72, v72
	v_exp_f32_e32 v73, v73
	v_pk_mul_f32 v[76:77], v[126:127], v[130:131]
	s_movk_i32 s15, 0x1600
	v_add_f32_e32 v72, 1.0, v72
	v_add_f32_e32 v73, 1.0, v73
	v_rcp_f32_e32 v72, v72
	v_rcp_f32_e32 v73, v73
	s_nop 0
	v_pk_mul_f32 v[72:73], v[76:77], v[72:73]
	s_nop 0
	v_cvt_pk_bf16_f32 v72, v72, v73
	v_mul_f32_e32 v73, 0xbfb8aa3b, v104
	v_exp_f32_e32 v73, v73
	v_pk_mul_f32 v[76:77], v[108:109], v[104:105]
	v_add_f32_e32 v73, 1.0, v73
	v_rcp_f32_e32 v80, v73
	v_mul_f32_e32 v73, 0xbfb8aa3b, v105
	v_exp_f32_e32 v73, v73
	s_nop 0
	v_add_f32_e32 v73, 1.0, v73
	v_rcp_f32_e32 v81, v73
	s_nop 0
	v_pk_mul_f32 v[76:77], v[76:77], v[80:81]
	s_nop 0
	v_cvt_pk_bf16_f32 v73, v76, v77
	v_mad_i64_i32 v[76:77], s[94:95], v168, s15, v[78:79]
	ds_write_b64 v251, v[72:73] offset:1536

; __device__ __forceinline__ unsigned cvtpk(float lo, float hi) { f32x2_t v = {lo, hi}; bf16x2_t b = __builtin_convertvector(v, bf16x2_t); return __builtin_bit_cast(unsigned, b); }
;     __device__ __forceinline__ void operator()(f32x4 (&acc)[2][2][4][2], const Unit& u, int wr, int wc, int fr, int fq) const {
;     ...
;                         float a[2];
; #pragma unroll
;                         for (int jj = 0; jj < 2; ++jj) { const float g = uu[0][jj]; a[jj] = g * uu[1][jj] * __builtin_amdgcn_rcpf(1.f + __builtin_amdgcn_exp2f(-g * LOG2E)); }
;                         const unsigned pk = cvtpk(a[0], a[1]);
;                         if (jh == 0) stash[ai][m] = pk;
;                         else if (rr >= 1 && rr <= 62 && tok < ntok) { u32x2 w; w.x = stash[ai][m]; w.y = pk; *(u32x2*)(obase + (size_t)tok * FFN + 4 * n) = w; }
.LBB0_855:
	s_mov_b64 s[82:83], s[46:47]
	s_and_saveexec_b64 s[80:81], s[40:41]
	s_cbranch_execz .LBB0_857
	ds_read_b64 v[226:227], v250
	v_mul_f32_e32 v83, 0xbfb8aa3b, v96
	v_exp_f32_e32 v83, v83
	v_pk_mul_f32 v[100:101], v[100:101], v[96:97]
	v_pk_mul_f32 v[64:65], v[64:65], v[56:57]
	v_mul_f32_e32 v56, 0xbfb8aa3b, v56
	v_add_f32_e32 v83, 1.0, v83
	v_rcp_f32_e32 v96, v83
	v_mul_f32_e32 v83, 0xbfb8aa3b, v97
	v_mul_f32_e32 v57, 0xbfb8aa3b, v57
	v_exp_f32_e32 v83, v83
	v_exp_f32_e32 v56, v56
	v_exp_f32_e32 v57, v57
	s_movk_i32 s15, 0x1600
	v_add_f32_e32 v83, 1.0, v83
	v_add_f32_e32 v56, 1.0, v56
	v_add_f32_e32 v57, 1.0, v57
	v_rcp_f32_e32 v97, v83
	v_rcp_f32_e32 v56, v56
	v_rcp_f32_e32 v57, v57
	v_pk_mul_f32 v[96:97], v[100:101], v[96:97]
	s_nop 0
	v_cvt_pk_bf16_f32 v96, v96, v97
	v_pk_mul_f32 v[56:57], v[64:65], v[56:57]
	s_nop 0
	v_cvt_pk_bf16_f32 v97, v56, v57
	v_mad_i64_i32 v[56:57], s[40:41], v249, s15, v[78:79]
	v_mov_b32_e32 v228, v96
	v_mov_b32_e32 v229, v97
	s_waitcnt lgkmcnt(0)
	global_store_dwordx4 v[56:57], v[226:229], off

; __device__ __forceinline__ unsigned cvtpk(float lo, float hi) { f32x2_t v = {lo, hi}; bf16x2_t b = __builtin_convertvector(v, bf16x2_t); return __builtin_bit_cast(unsigned, b); }
;     __device__ __forceinline__ void operator()(f32x4 (&acc)[2][2][4][2], const Unit& u, int wr, int wc, int fr, int fq) const {
;     ...
;                         float a[2];
; #pragma unroll
;                         for (int jj = 0; jj < 2; ++jj) { const float g = uu[0][jj]; a[jj] = g * uu[1][jj] * __builtin_amdgcn_rcpf(1.f + __builtin_amdgcn_exp2f(-g * LOG2E)); }
;                         const unsigned pk = cvtpk(a[0], a[1]);
;                         if (jh == 0) stash[ai][m] = pk;
;                         else if (rr >= 1 && rr <= 62 && tok < ntok) { u32x2 w; w.x = stash[ai][m]; w.y = pk; *(u32x2*)(obase + (size_t)tok * FFN + 4 * n) = w; }
.LBB0_859:
	s_and_saveexec_b64 s[40:41], s[90:91]
	s_cbranch_execz .LBB0_861
	ds_read_b64 v[226:227], v250 offset:512
	v_mul_f32_e32 v68, 0xbfb8aa3b, v88
	v_mul_f32_e32 v69, 0xbfb8aa3b, v89
	v_pk_mul_f32 v[64:65], v[64:65], v[56:57]
	v_mul_f32_e32 v56, 0xbfb8aa3b, v56
	v_mul_f32_e32 v57, 0xbfb8aa3b, v57
	v_exp_f32_e32 v68, v68
	v_exp_f32_e32 v69, v69
	v_exp_f32_e32 v56, v56
	v_exp_f32_e32 v57, v57
	v_add_f32_e32 v68, 1.0, v68
	v_add_f32_e32 v69, 1.0, v69
	v_add_f32_e32 v56, 1.0, v56
	v_add_f32_e32 v57, 1.0, v57
	v_rcp_f32_e32 v68, v68
	v_rcp_f32_e32 v69, v69
	v_rcp_f32_e32 v56, v56
	v_rcp_f32_e32 v57, v57
	v_pk_mul_f32 v[60:61], v[92:93], v[88:89]
	s_movk_i32 s15, 0x1600
	v_pk_mul_f32 v[60:61], v[60:61], v[68:69]
	v_pk_mul_f32 v[56:57], v[64:65], v[56:57]
	v_cvt_pk_bf16_f32 v60, v60, v61
	v_cvt_pk_bf16_f32 v61, v56, v57
	v_mad_i64_i32 v[56:57], s[76:77], v248, s15, v[78:79]
	v_mov_b32_e32 v228, v60
	v_mov_b32_e32 v229, v61
	s_waitcnt lgkmcnt(0)
	global_store_dwordx4 v[56:57], v[226:229], off

; __device__ __forceinline__ unsigned cvtpk(float lo, float hi) { f32x2_t v = {lo, hi}; bf16x2_t b = __builtin_convertvector(v, bf16x2_t); return __builtin_bit_cast(unsigned, b); }
;     __device__ __forceinline__ void operator()(f32x4 (&acc)[2][2][4][2], const Unit& u, int wr, int wc, int fr, int fq) const {
;     ...
;                         float a[2];
; #pragma unroll
;                         for (int jj = 0; jj < 2; ++jj) { const float g = uu[0][jj]; a[jj] = g * uu[1][jj] * __builtin_amdgcn_rcpf(1.f + __builtin_amdgcn_exp2f(-g * LOG2E)); }
;                         const unsigned pk = cvtpk(a[0], a[1]);
;                         if (jh == 0) stash[ai][m] = pk;
;                         else if (rr >= 1 && rr <= 62 && tok < ntok) { u32x2 w; w.x = stash[ai][m]; w.y = pk; *(u32x2*)(obase + (size_t)tok * FFN + 4 * n) = w; }
.LBB0_863:
	s_and_saveexec_b64 s[40:41], s[88:89]
	s_cbranch_execz .LBB0_865
	ds_read_b64 v[226:227], v250 offset:8192
	v_mul_f32_e32 v34, 0xbfb8aa3b, v46
	v_mul_f32_e32 v35, 0xbfb8aa3b, v47
	v_exp_f32_e32 v34, v34
	v_exp_f32_e32 v35, v35
	v_pk_mul_f32 v[30:31], v[50:51], v[46:47]
	s_movk_i32 s15, 0x1600
	v_add_f32_e32 v34, 1.0, v34
	v_add_f32_e32 v35, 1.0, v35
	v_rcp_f32_e32 v34, v34
	v_rcp_f32_e32 v35, v35
	s_nop 0
	v_pk_mul_f32 v[30:31], v[30:31], v[34:35]
	s_nop 0
	v_cvt_pk_bf16_f32 v30, v30, v31
	v_mul_f32_e32 v31, 0xbfb8aa3b, v56
	v_exp_f32_e32 v31, v31
	v_pk_mul_f32 v[34:35], v[60:61], v[56:57]
	v_add_f32_e32 v31, 1.0, v31
	v_rcp_f32_e32 v46, v31
	v_mul_f32_e32 v31, 0xbfb8aa3b, v57
	v_exp_f32_e32 v31, v31
	s_nop 0
	v_add_f32_e32 v31, 1.0, v31
	v_rcp_f32_e32 v47, v31
	s_nop 0
	v_pk_mul_f32 v[34:35], v[34:35], v[46:47]
	s_nop 0
	v_cvt_pk_bf16_f32 v31, v34, v35
	v_mad_i64_i32 v[34:35], s[72:73], v225, s15, v[78:79]
	v_mov_b32_e32 v228, v30
	v_mov_b32_e32 v229, v31
	s_waitcnt lgkmcnt(0)
	global_store_dwordx4 v[34:35], v[226:229], off

; __device__ __forceinline__ unsigned cvtpk(float lo, float hi) { f32x2_t v = {lo, hi}; bf16x2_t b = __builtin_convertvector(v, bf16x2_t); return __builtin_bit_cast(unsigned, b); }
;     __device__ __forceinline__ void operator()(f32x4 (&acc)[2][2][4][2], const Unit& u, int wr, int wc, int fr, int fq) const {
;     ...
;                         float a[2];
; #pragma unroll
;                         for (int jj = 0; jj < 2; ++jj) { const float g = uu[0][jj]; a[jj] = g * uu[1][jj] * __builtin_amdgcn_rcpf(1.f + __builtin_amdgcn_exp2f(-g * LOG2E)); }
;                         const unsigned pk = cvtpk(a[0], a[1]);
;                         if (jh == 0) stash[ai][m] = pk;
;                         else if (rr >= 1 && rr <= 62 && tok < ntok) { u32x2 w; w.x = stash[ai][m]; w.y = pk; *(u32x2*)(obase + (size_t)tok * FFN + 4 * n) = w; }
.LBB0_867:
	v_readlane_b32 s70, v254, 61
	s_mov_b32 s68, 0x40000
	v_readlane_b32 s71, v254, 62
	s_and_saveexec_b64 s[40:41], s[22:23]
	s_cbranch_execz .LBB0_869
	ds_read_b64 v[226:227], v250 offset:8704
	v_pk_mul_f32 v[40:41], v[42:43], v[38:39]
	v_mul_f32_e32 v38, 0xbfb8aa3b, v38
	v_mul_f32_e32 v39, 0xbfb8aa3b, v39
	v_pk_mul_f32 v[34:35], v[34:35], v[30:31]
	v_mul_f32_e32 v30, 0xbfb8aa3b, v30
	v_mul_f32_e32 v31, 0xbfb8aa3b, v31
	v_exp_f32_e32 v38, v38
	v_exp_f32_e32 v39, v39
	v_exp_f32_e32 v30, v30
	v_exp_f32_e32 v31, v31
	v_add_f32_e32 v38, 1.0, v38
	v_add_f32_e32 v39, 1.0, v39
	v_add_f32_e32 v30, 1.0, v30
	v_add_f32_e32 v31, 1.0, v31
	v_rcp_f32_e32 v38, v38
	v_rcp_f32_e32 v39, v39
	v_rcp_f32_e32 v30, v30
	v_rcp_f32_e32 v31, v31
	s_movk_i32 s15, 0x1600
	v_pk_mul_f32 v[38:39], v[40:41], v[38:39]
	v_pk_mul_f32 v[30:31], v[34:35], v[30:31]
	v_cvt_pk_bf16_f32 v38, v38, v39
	v_cvt_pk_bf16_f32 v39, v30, v31
	v_mad_i64_i32 v[30:31], s[22:23], v224, s15, v[78:79]
	v_mov_b32_e32 v228, v38
	v_mov_b32_e32 v229, v39
	s_waitcnt lgkmcnt(0)
	global_store_dwordx4 v[30:31], v[226:229], off

; __device__ __forceinline__ unsigned cvtpk(float lo, float hi) { f32x2_t v = {lo, hi}; bf16x2_t b = __builtin_convertvector(v, bf16x2_t); return __builtin_bit_cast(unsigned, b); }
;     __device__ __forceinline__ void operator()(f32x4 (&acc)[2][2][4][2], const Unit& u, int wr, int wc, int fr, int fq) const {
;     ...
;                         float a[2];
; #pragma unroll
;                         for (int jj = 0; jj < 2; ++jj) { const float g = uu[0][jj]; a[jj] = g * uu[1][jj] * __builtin_amdgcn_rcpf(1.f + __builtin_amdgcn_exp2f(-g * LOG2E)); }
;                         const unsigned pk = cvtpk(a[0], a[1]);
;                         if (jh == 0) stash[ai][m] = pk;
;                         else if (rr >= 1 && rr <= 62 && tok < ntok) { u32x2 w; w.x = stash[ai][m]; w.y = pk; *(u32x2*)(obase + (size_t)tok * FFN + 4 * n) = w; }
.LBB0_871:
	s_and_saveexec_b64 s[22:23], s[20:21]
	s_cbranch_execz .LBB0_873
	ds_read_b64 v[226:227], v251
	v_pk_mul_f32 v[26:27], v[26:27], v[22:23]
	v_mul_f32_e32 v22, 0xbfb8aa3b, v22
	v_mul_f32_e32 v23, 0xbfb8aa3b, v23
	v_exp_f32_e32 v22, v22
	v_exp_f32_e32 v23, v23
	s_movk_i32 s15, 0x1600
	v_add_f32_e32 v22, 1.0, v22
	v_add_f32_e32 v23, 1.0, v23
	v_rcp_f32_e32 v22, v22
	v_rcp_f32_e32 v23, v23
	s_nop 0
	v_pk_mul_f32 v[22:23], v[26:27], v[22:23]
	s_nop 0
	v_cvt_pk_bf16_f32 v22, v22, v23
	v_mul_f32_e32 v23, 0xbfb8aa3b, v32
	v_exp_f32_e32 v23, v23
	v_pk_mul_f32 v[26:27], v[36:37], v[32:33]
	v_add_f32_e32 v23, 1.0, v23
	v_rcp_f32_e32 v32, v23
	v_mul_f32_e32 v23, 0xbfb8aa3b, v33
	v_exp_f32_e32 v23, v23
	s_nop 0
	v_add_f32_e32 v23, 1.0, v23
	v_rcp_f32_e32 v33, v23
	s_nop 0
	v_pk_mul_f32 v[26:27], v[26:27], v[32:33]
	s_nop 0
	v_cvt_pk_bf16_f32 v23, v26, v27
	v_mad_i64_i32 v[26:27], s[20:21], v178, s15, v[78:79]
	v_mov_b32_e32 v228, v22
	v_mov_b32_e32 v229, v23
	s_waitcnt lgkmcnt(0)
	global_store_dwordx4 v[26:27], v[226:229], off

; __device__ __forceinline__ unsigned cvtpk(float lo, float hi) { f32x2_t v = {lo, hi}; bf16x2_t b = __builtin_convertvector(v, bf16x2_t); return __builtin_bit_cast(unsigned, b); }
;     __device__ __forceinline__ void operator()(f32x4 (&acc)[2][2][4][2], const Unit& u, int wr, int wc, int fr, int fq) const {
;     ...
;                         float a[2];
; #pragma unroll
;                         for (int jj = 0; jj < 2; ++jj) { const float g = uu[0][jj]; a[jj] = g * uu[1][jj] * __builtin_amdgcn_rcpf(1.f + __builtin_amdgcn_exp2f(-g * LOG2E)); }
;                         const unsigned pk = cvtpk(a[0], a[1]);
;                         if (jh == 0) stash[ai][m] = pk;
;                         else if (rr >= 1 && rr <= 62 && tok < ntok) { u32x2 w; w.x = stash[ai][m]; w.y = pk; *(u32x2*)(obase + (size_t)tok * FFN + 4 * n) = w; }
.LBB0_875:
	s_and_saveexec_b64 s[20:21], s[86:87]
	s_cbranch_execz .LBB0_877
	ds_read_b64 v[226:227], v251 offset:512
	v_pk_mul_f32 v[18:19], v[18:19], v[10:11]
	v_mul_f32_e32 v10, 0xbfb8aa3b, v10
	v_mul_f32_e32 v11, 0xbfb8aa3b, v11
	v_exp_f32_e32 v10, v10
	v_exp_f32_e32 v11, v11
	s_movk_i32 s15, 0x1600
	v_add_f32_e32 v10, 1.0, v10
	v_add_f32_e32 v11, 1.0, v11
	v_rcp_f32_e32 v10, v10
	v_rcp_f32_e32 v11, v11
	s_nop 0
	v_pk_mul_f32 v[10:11], v[18:19], v[10:11]
	s_nop 0
	v_cvt_pk_bf16_f32 v10, v10, v11
	v_mul_f32_e32 v11, 0xbfb8aa3b, v22
	v_exp_f32_e32 v11, v11
	v_pk_mul_f32 v[18:19], v[26:27], v[22:23]
	v_add_f32_e32 v11, 1.0, v11
	v_rcp_f32_e32 v22, v11
	v_mul_f32_e32 v11, 0xbfb8aa3b, v23
	v_exp_f32_e32 v11, v11
	s_nop 0
	v_add_f32_e32 v11, 1.0, v11
	v_rcp_f32_e32 v23, v11
	s_nop 0
	v_pk_mul_f32 v[18:19], v[18:19], v[22:23]
	s_nop 0
	v_cvt_pk_bf16_f32 v11, v18, v19
	v_mad_i64_i32 v[18:19], s[22:23], v170, s15, v[78:79]
	v_mov_b32_e32 v228, v10
	v_mov_b32_e32 v229, v11
	s_waitcnt lgkmcnt(0)
	global_store_dwordx4 v[18:19], v[226:229], off

; __device__ __forceinline__ unsigned cvtpk(float lo, float hi) { f32x2_t v = {lo, hi}; bf16x2_t b = __builtin_convertvector(v, bf16x2_t); return __builtin_bit_cast(unsigned, b); }
;     __device__ __forceinline__ void operator()(f32x4 (&acc)[2][2][4][2], const Unit& u, int wr, int wc, int fr, int fq) const {
;     ...
;                         float a[2];
; #pragma unroll
;                         for (int jj = 0; jj < 2; ++jj) { const float g = uu[0][jj]; a[jj] = g * uu[1][jj] * __builtin_amdgcn_rcpf(1.f + __builtin_amdgcn_exp2f(-g * LOG2E)); }
;                         const unsigned pk = cvtpk(a[0], a[1]);
;                         if (jh == 0) stash[ai][m] = pk;
;                         else if (rr >= 1 && rr <= 62 && tok < ntok) { u32x2 w; w.x = stash[ai][m]; w.y = pk; *(u32x2*)(obase + (size_t)tok * FFN + 4 * n) = w; }
.LBB0_879:
	s_and_saveexec_b64 s[20:21], s[84:85]
	s_cbranch_execz .LBB0_881
	ds_read_b64 v[226:227], v251 offset:1024
	v_pk_mul_f32 v[6:7], v[6:7], v[2:3]
	v_mul_f32_e32 v2, 0xbfb8aa3b, v2
	v_mul_f32_e32 v3, 0xbfb8aa3b, v3
	v_exp_f32_e32 v2, v2
	v_exp_f32_e32 v3, v3
	s_movk_i32 s15, 0x1600
	v_add_f32_e32 v2, 1.0, v2
	v_add_f32_e32 v3, 1.0, v3
	v_rcp_f32_e32 v2, v2
	v_rcp_f32_e32 v3, v3
	s_nop 0
	v_pk_mul_f32 v[2:3], v[6:7], v[2:3]
	s_nop 0
	v_cvt_pk_bf16_f32 v2, v2, v3
	v_mul_f32_e32 v3, 0xbfb8aa3b, v10
	v_exp_f32_e32 v3, v3
	v_pk_mul_f32 v[6:7], v[18:19], v[10:11]
	v_add_f32_e32 v3, 1.0, v3
	v_rcp_f32_e32 v10, v3
	v_mul_f32_e32 v3, 0xbfb8aa3b, v11
	v_exp_f32_e32 v3, v3
	s_nop 0
	v_add_f32_e32 v3, 1.0, v3
	v_rcp_f32_e32 v11, v3
	s_nop 0
	v_pk_mul_f32 v[6:7], v[6:7], v[10:11]
	s_nop 0
	v_cvt_pk_bf16_f32 v3, v6, v7
	v_mad_i64_i32 v[6:7], s[22:23], v169, s15, v[78:79]
	v_mov_b32_e32 v228, v2
	v_mov_b32_e32 v229, v3
	s_waitcnt lgkmcnt(0)
	global_store_dwordx4 v[6:7], v[226:229], off

; __device__ __forceinline__ unsigned cvtpk(float lo, float hi) { f32x2_t v = {lo, hi}; bf16x2_t b = __builtin_convertvector(v, bf16x2_t); return __builtin_bit_cast(unsigned, b); }
;     __device__ __forceinline__ void operator()(f32x4 (&acc)[2][2][4][2], const Unit& u, int wr, int wc, int fr, int fq) const {
;     ...
;                         float a[2];
; #pragma unroll
;                         for (int jj = 0; jj < 2; ++jj) { const float g = uu[0][jj]; a[jj] = g * uu[1][jj] * __builtin_amdgcn_rcpf(1.f + __builtin_amdgcn_exp2f(-g * LOG2E)); }
;                         const unsigned pk = cvtpk(a[0], a[1]);
;                         if (jh == 0) stash[ai][m] = pk;
;                         else if (rr >= 1 && rr <= 62 && tok < ntok) { u32x2 w; w.x = stash[ai][m]; w.y = pk; *(u32x2*)(obase + (size_t)tok * FFN + 4 * n) = w; }
.LBB0_883:
	s_and_saveexec_b64 s[20:21], s[6:7]
	s_cbranch_execz .LBB0_885
	ds_read_b64 v[226:227], v251 offset:1536
	v_mul_f32_e32 v4, 0xbfb8aa3b, v70
	v_mul_f32_e32 v5, 0xbfb8aa3b, v71
	v_exp_f32_e32 v4, v4
	v_exp_f32_e32 v5, v5
	v_pk_mul_f32 v[2:3], v[74:75], v[70:71]
	s_movk_i32 s6, 0x1600
	v_add_f32_e32 v4, 1.0, v4
	v_add_f32_e32 v5, 1.0, v5
	v_rcp_f32_e32 v4, v4
	v_rcp_f32_e32 v5, v5
	s_nop 0
	v_pk_mul_f32 v[2:3], v[2:3], v[4:5]
	s_nop 0
	v_cvt_pk_bf16_f32 v2, v2, v3
	v_mul_f32_e32 v3, 0xbfb8aa3b, v54
	v_exp_f32_e32 v3, v3
	v_pk_mul_f32 v[4:5], v[58:59], v[54:55]
	v_add_f32_e32 v3, 1.0, v3
	v_rcp_f32_e32 v6, v3
	v_mul_f32_e32 v3, 0xbfb8aa3b, v55
	v_exp_f32_e32 v3, v3
	s_nop 0
	v_add_f32_e32 v3, 1.0, v3
	v_rcp_f32_e32 v7, v3
	s_nop 0
	v_pk_mul_f32 v[4:5], v[4:5], v[6:7]
	s_nop 0
	v_cvt_pk_bf16_f32 v3, v4, v5
	v_mad_i64_i32 v[4:5], s[6:7], v168, s6, v[78:79]
	v_mov_b32_e32 v228, v2
	v_mov_b32_e32 v229, v3
	s_waitcnt lgkmcnt(0)
	global_store_dwordx4 v[4:5], v[226:229], off

; __global__ void __launch_bounds__(512, 2) fwd_kernel(Params p) {
;     extern __shared__ __attribute__((aligned(16))) unsigned char smem[];
	.amdhsa_kernel _Z10fwd_kernel6Params
		.amdhsa_group_segment_fixed_size 16384
		.amdhsa_private_segment_fixed_size 0
		.amdhsa_kernarg_size 440
		.amdhsa_user_sgpr_count 2
		.amdhsa_user_sgpr_dispatch_ptr 0
		.amdhsa_user_sgpr_queue_ptr 0
		.amdhsa_user_sgpr_kernarg_segment_ptr 1
		.amdhsa_user_sgpr_dispatch_id 0
		.amdhsa_user_sgpr_kernarg_preload_length 0
		.amdhsa_user_sgpr_kernarg_preload_offset 0
		.amdhsa_user_sgpr_private_segment_size 0
		.amdhsa_uses_dynamic_stack 0
		.amdhsa_enable_private_segment 0
		.amdhsa_system_sgpr_workgroup_id_x 1
		.amdhsa_system_sgpr_workgroup_id_y 0
		.amdhsa_system_sgpr_workgroup_id_z 0
		.amdhsa_system_sgpr_workgroup_info 0
		.amdhsa_system_vgpr_workitem_id 2
		.amdhsa_next_free_vgpr 256
		.amdhsa_next_free_sgpr 98
		.amdhsa_accum_offset 256
		.amdhsa_reserve_vcc 1
		.amdhsa_float_round_mode_32 0
		.amdhsa_float_round_mode_16_64 0
		.amdhsa_float_denorm_mode_32 3
		.amdhsa_float_denorm_mode_16_64 3
		.amdhsa_dx10_clamp 1
		.amdhsa_ieee_mode 1
		.amdhsa_fp16_overflow 0
		.amdhsa_tg_split 0
		.amdhsa_exception_fp_ieee_invalid_op 0
		.amdhsa_exception_fp_denorm_src 0
		.amdhsa_exception_fp_ieee_div_zero 0
		.amdhsa_exception_fp_ieee_overflow 0
		.amdhsa_exception_fp_ieee_underflow 0
		.amdhsa_exception_fp_ieee_inexact 0
		.amdhsa_exception_int_div_zero 0
	.end_amdhsa_kernel

; __global__ void __launch_bounds__(512, 2) fwd_kernel(Params p) {
;     extern __shared__ __attribute__((aligned(16))) unsigned char smem[];
amdhsa.kernels:
  - .agpr_count:     0
    .args:
      - .offset:         0
        .size:           184
        .value_kind:     by_value
      - .offset:         184
        .size:           4
        .value_kind:     hidden_block_count_x
      - .offset:         188
        .size:           4
        .value_kind:     hidden_block_count_y
      - .offset:         192
        .size:           4
        .value_kind:     hidden_block_count_z
      - .offset:         196
        .size:           2
        .value_kind:     hidden_group_size_x
      - .offset:         198
        .size:           2
        .value_kind:     hidden_group_size_y
      - .offset:         200
        .size:           2
        .value_kind:     hidden_group_size_z
      - .offset:         202
        .size:           2
        .value_kind:     hidden_remainder_x
      - .offset:         204
        .size:           2
        .value_kind:     hidden_remainder_y
      - .offset:         206
        .size:           2
        .value_kind:     hidden_remainder_z
      - .offset:         224
        .size:           8
        .value_kind:     hidden_global_offset_x
      - .offset:         232
        .size:           8
        .value_kind:     hidden_global_offset_y
      - .offset:         240
        .size:           8
        .value_kind:     hidden_global_offset_z
      - .offset:         248
        .size:           2
        .value_kind:     hidden_grid_dims
      - .offset:         272
        .size:           8
        .value_kind:     hidden_multigrid_sync_arg
      - .offset:         304
        .size:           4
        .value_kind:     hidden_dynamic_lds_size
    .group_segment_fixed_size: 16384
    .kernarg_segment_align: 8
    .kernarg_segment_size: 440
    .language:       OpenCL C
    .language_version:
      - 2
      - 0
    .max_flat_workgroup_size: 512
    .name:           _Z10fwd_kernel6Params
    .private_segment_fixed_size: 0
    .sgpr_count:     104
    .sgpr_spill_count: 236
    .symbol:         _Z10fwd_kernel6Params.kd
    .uniform_work_group_size: 1
    .uses_dynamic_stack: false
    .vgpr_count:     256
    .vgpr_spill_count: 0
    .wavefront_size: 64
